# x tile touched into L2/MALL by waves 4-7 while wave 0 polls the GEMM2->GEMM3 panel sync
# baseline (speedup 1.0000x reference)
.LBB0_454:
	s_cmp_gt_i32 s69, 7
	s_cselect_b64 s[4:5], -1, 0
	s_and_b64 s[6:7], s[6:7], s[4:5]
	s_andn2_b64 vcc, exec, s[6:7]
	s_cbranch_vccnz .LBB0_477
	s_waitcnt vmcnt(0)
	v_readlane_b32 s6, v251, 0
	v_readlane_b32 s7, v251, 1
	s_andn2_b64 vcc, exec, s[6:7]
	s_waitcnt vmcnt(0)
	s_barrier
	s_cmp_lt_u32 s62, 4
	s_cbranch_scc1 .Lxpf_skip
	s_and_b32 s98, s2, 7
	s_lshl_b32 s98, s98, 3
	s_bfe_u32 s99, s2, 0x30003
	s_or_b32 s98, s98, s99
	s_lshl_b32 s98, s98, 20
	s_lshr_b32 s99, s2, 6
	s_lshl_b32 s99, s99, 10
	s_add_u32 s98, s98, s99
	s_add_u32 s98, s36, s98
	s_addc_u32 s99, s37, 0
	v_mbcnt_lo_u32_b32 v253, -1, 0
	v_mbcnt_hi_u32_b32 v253, -1, v253
	s_sub_i32 s100, s62, 4
	s_lshl_b32 s100, s100, 6
	v_add_u32_e32 v253, s100, v253
	v_lshlrev_b32_e32 v253, 12, v253
	global_load_dword v252, v253, s[98:99]
	global_load_dword v252, v253, s[98:99] offset:128
	global_load_dword v252, v253, s[98:99] offset:256
	global_load_dword v252, v253, s[98:99] offset:384
	global_load_dword v252, v253, s[98:99] offset:512
	global_load_dword v252, v253, s[98:99] offset:640
	global_load_dword v252, v253, s[98:99] offset:768
	global_load_dword v252, v253, s[98:99] offset:896
.Lxpf_skip:
	s_cbranch_vccnz .LBB0_476
	v_mbcnt_lo_u32_b32 v0, -1, 0
	v_mbcnt_hi_u32_b32 v0, -1, v0
	s_nop 0
	v_cmp_eq_u32_e32 vcc, 0, v0
	s_and_saveexec_b64 s[6:7], vcc
	s_cbranch_execz .LBB0_475
	v_readlane_b32 s8, v251, 24
	v_readlane_b32 s9, v251, 25
	s_andn2_b64 vcc, exec, s[8:9]
	s_cbranch_vccnz .LBB0_459
	buffer_wbl2 sc1
